# GEMM swiglu epilogues (P7,P15): 8 rowscale loads hoisted to epilogue start, single wait, no per-group vmcnt(0) ladder
# speedup vs baseline: 1.0016x; 1.0006x over previous
.LBB0_627:
	v_lshl_add_u32 v152, s0, 8, v154
	v_ashrrev_i32_e32 v153, 31, v152
	v_lshlrev_b64 v[150:151], 6, v[152:153]
	v_lshl_add_u64 v[150:151], v[140:141], 0, v[150:151]
	global_load_dwordx4 v[164:167], v[150:151], off
	global_load_dwordx4 v[188:191], v[150:151], off offset:1024
	global_load_dwordx4 v[192:195], v[150:151], off offset:2048
	global_load_dwordx4 v[196:199], v[150:151], off offset:3072
	v_mov_b32_e32 v216, 0x2000
	v_mov_b32_e32 v217, 0
	v_lshl_add_u64 v[216:217], v[150:151], 0, v[216:217]
	global_load_dwordx4 v[200:203], v[216:217], off
	global_load_dwordx4 v[204:207], v[216:217], off offset:1024
	global_load_dwordx4 v[208:211], v[216:217], off offset:2048
	global_load_dwordx4 v[212:215], v[216:217], off offset:3072
	v_and_b32_e32 v163, 64, v161
	v_xor_b32_e32 v153, 16, v161
	v_pk_mul_f32 v[170:171], v[114:115], v[122:123]
	v_add_u32_e32 v122, 64, v163
	v_cmp_lt_i32_e32 vcc, v153, v122
	v_pk_mul_f32 v[172:173], v[112:113], v[120:121]
	v_xor_b32_e32 v174, 32, v161
	v_cndmask_b32_e32 v120, v161, v153, vcc
	v_lshlrev_b32_e32 v123, 2, v120
	v_cmp_lt_i32_e32 vcc, v174, v122
	v_pk_mul_f32 v[126:127], v[118:119], v[126:127]
	v_pk_mul_f32 v[124:125], v[116:117], v[124:125]
	v_cndmask_b32_e32 v122, v161, v174, vcc
	v_lshlrev_b32_e32 v122, 2, v122
	v_lshl_or_b32 v168, s1, 7, v156
	v_ashrrev_i32_e32 v169, 31, v168
	v_mov_b64_e32 v[150:151], s[10:11]
	v_pk_mul_f32 v[110:111], v[102:103], v[110:111]
	v_pk_mul_f32 v[108:109], v[100:101], v[108:109]
	v_pk_mul_f32 v[106:107], v[98:99], v[106:107]
	v_pk_mul_f32 v[104:105], v[96:97], v[104:105]
	v_pk_mul_f32 v[94:95], v[86:87], v[94:95]
	v_pk_mul_f32 v[92:93], v[84:85], v[92:93]
	v_pk_mul_f32 v[90:91], v[82:83], v[90:91]
	v_pk_mul_f32 v[88:89], v[80:81], v[88:89]
	v_pk_mul_f32 v[78:79], v[70:71], v[78:79]
	v_pk_mul_f32 v[76:77], v[68:69], v[76:77]
	v_pk_mul_f32 v[74:75], v[66:67], v[74:75]
	v_pk_mul_f32 v[72:73], v[64:65], v[72:73]
	v_pk_mul_f32 v[62:63], v[54:55], v[62:63]
	v_pk_mul_f32 v[60:61], v[52:53], v[60:61]
	v_pk_mul_f32 v[58:59], v[50:51], v[58:59]
	v_pk_mul_f32 v[56:57], v[48:49], v[56:57]
	v_pk_mul_f32 v[46:47], v[38:39], v[46:47]
	v_pk_mul_f32 v[44:45], v[36:37], v[44:45]
	v_pk_mul_f32 v[42:43], v[34:35], v[42:43]
	v_pk_mul_f32 v[40:41], v[32:33], v[40:41]
	v_pk_mul_f32 v[30:31], v[22:23], v[30:31]
	v_pk_mul_f32 v[28:29], v[20:21], v[28:29]
	v_pk_mul_f32 v[26:27], v[18:19], v[26:27]
	v_pk_mul_f32 v[24:25], v[16:17], v[24:25]
	v_pk_mul_f32 v[14:15], v[6:7], v[14:15]
	v_pk_mul_f32 v[12:13], v[4:5], v[12:13]
	v_pk_mul_f32 v[10:11], v[2:3], v[10:11]
	v_pk_mul_f32 v[8:9], v[0:1], v[8:9]
	s_waitcnt vmcnt(0)
	v_mov_b32_e32 v120, v165
	v_mov_b32_e32 v121, v166
	v_mov_b32_e32 v165, v167
	v_pk_add_f32 v[120:121], v[120:121], v[164:165]
	v_or_b32_e32 v166, 16, v152
	v_add_f32_e32 v120, v120, v121
	ds_bpermute_b32 v121, v123, v120
	v_ashrrev_i32_e32 v167, 31, v166
	v_mad_i64_i32 v[164:165], s[0:1], v152, s49, v[150:151]
	s_waitcnt lgkmcnt(0)
	v_add_f32_e32 v153, v120, v121
	ds_bpermute_b32 v163, v122, v153
	v_lshlrev_b64 v[120:121], 1, v[168:169]
	v_lshlrev_b64 v[168:169], 6, v[166:167]
	v_lshl_add_u64 v[164:165], v[164:165], 0, v[120:121]
	v_lshl_add_u64 v[168:169], v[140:141], 0, v[168:169]
	s_waitcnt lgkmcnt(0)
	v_add_f32_e32 v153, v153, v163
	v_fmamk_f32 v153, v153, 0x3a800000, v162
	v_mul_f32_e32 v163, 0x4b800000, v153
	v_cmp_gt_f32_e32 vcc, s52, v153
	s_nop 1
	v_cndmask_b32_e32 v153, v153, v163, vcc
	v_rsq_f32_e32 v153, v153
	s_nop 0
	v_mul_f32_e32 v163, 0x45800000, v153
	v_cndmask_b32_e32 v153, v153, v163, vcc
	v_mul_f32_e32 v163, 0xbfb8aa3b, v153
	v_mul_f32_e32 v116, v116, v163
	v_mul_f32_e32 v117, v117, v163
	v_mul_f32_e32 v118, v118, v163
	v_mul_f32_e32 v119, v119, v163
	v_mul_f32_e32 v112, v112, v163
	v_mul_f32_e32 v113, v113, v163
	v_mul_f32_e32 v114, v114, v163
	v_mul_f32_e32 v115, v115, v163
	v_exp_f32_e32 v116, v116
	v_exp_f32_e32 v117, v117
	v_exp_f32_e32 v118, v118
	v_exp_f32_e32 v119, v119
	v_exp_f32_e32 v112, v112
	v_exp_f32_e32 v113, v113
	v_exp_f32_e32 v114, v114
	v_exp_f32_e32 v115, v115
	v_mul_f32_e32 v174, v153, v153
	v_add_f32_e32 v116, 1.0, v116
	v_add_f32_e32 v117, 1.0, v117
	v_add_f32_e32 v118, 1.0, v118
	v_add_f32_e32 v119, 1.0, v119
	v_add_f32_e32 v153, 1.0, v112
	v_add_f32_e32 v163, 1.0, v113
	v_add_f32_e32 v167, 1.0, v114
	v_add_f32_e32 v175, 1.0, v115
	v_rcp_f32_e32 v112, v116
	v_rcp_f32_e32 v113, v117
	v_rcp_f32_e32 v114, v118
	v_rcp_f32_e32 v115, v119
	v_rcp_f32_e32 v116, v153
	v_rcp_f32_e32 v117, v163
	v_rcp_f32_e32 v118, v167
	v_rcp_f32_e32 v119, v175
	v_pk_mul_f32 v[112:113], v[174:175], v[112:113] op_sel_hi:[0,1]
	v_pk_mul_f32 v[114:115], v[174:175], v[114:115] op_sel_hi:[0,1]
	v_pk_mul_f32 v[116:117], v[174:175], v[116:117] op_sel_hi:[0,1]
	v_pk_mul_f32 v[118:119], v[174:175], v[118:119] op_sel_hi:[0,1]
	v_pk_mul_f32 v[112:113], v[124:125], v[112:113]
	v_pk_mul_f32 v[114:115], v[126:127], v[114:115]
	v_pk_mul_f32 v[116:117], v[172:173], v[116:117]
	v_pk_mul_f32 v[118:119], v[170:171], v[118:119]
	v_cvt_pk_bf16_f32 v112, v112, v113
	v_cvt_pk_bf16_f32 v113, v114, v115
	v_cvt_pk_bf16_f32 v114, v116, v117
	v_cvt_pk_bf16_f32 v115, v118, v119
	global_store_dwordx4 v[164:165], v[112:115], off
	s_nop 1
	v_mov_b32_e32 v112, v188
	v_mov_b32_e32 v113, v189
	v_mov_b32_e32 v114, v190
	v_mov_b32_e32 v115, v191
	v_mov_b32_e32 v116, v113
	v_mov_b32_e32 v117, v114
	v_mov_b32_e32 v113, v115
	v_pk_add_f32 v[112:113], v[116:117], v[112:113]
	v_mad_i64_i32 v[114:115], s[0:1], v166, s49, v[150:151]
	v_add_f32_e32 v112, v112, v113
	ds_bpermute_b32 v113, v123, v112
	v_lshl_add_u64 v[114:115], v[114:115], 0, v[120:121]
	s_waitcnt lgkmcnt(0)
	v_add_f32_e32 v116, v112, v113
	ds_bpermute_b32 v117, v122, v116
	v_or_b32_e32 v112, 32, v152
	v_ashrrev_i32_e32 v113, 31, v112
	s_waitcnt lgkmcnt(0)
	v_add_f32_e32 v116, v116, v117
	v_fmamk_f32 v116, v116, 0x3a800000, v162
	v_mul_f32_e32 v117, 0x4b800000, v116
	v_cmp_gt_f32_e32 vcc, s52, v116
	s_nop 1
	v_cndmask_b32_e32 v116, v116, v117, vcc
	v_rsq_f32_e32 v118, v116
	v_lshlrev_b64 v[116:117], 6, v[112:113]
	v_lshl_add_u64 v[116:117], v[140:141], 0, v[116:117]
	v_mul_f32_e32 v113, 0x45800000, v118
	v_cndmask_b32_e32 v113, v118, v113, vcc
	v_mul_f32_e32 v119, 0xbfb8aa3b, v113
	v_mul_f32_e32 v100, v100, v119
	v_mul_f32_e32 v101, v101, v119
	v_mul_f32_e32 v102, v102, v119
	v_mul_f32_e32 v103, v103, v119
	v_mul_f32_e32 v96, v96, v119
	v_mul_f32_e32 v97, v97, v119
	v_mul_f32_e32 v98, v98, v119
	v_mul_f32_e32 v99, v99, v119
	v_exp_f32_e32 v100, v100
	v_exp_f32_e32 v101, v101
	v_exp_f32_e32 v102, v102
	v_exp_f32_e32 v103, v103
	v_exp_f32_e32 v96, v96
	v_exp_f32_e32 v97, v97
	v_exp_f32_e32 v98, v98
	v_exp_f32_e32 v99, v99
	v_mul_f32_e32 v118, v113, v113
	v_add_f32_e32 v100, 1.0, v100
	v_add_f32_e32 v101, 1.0, v101
	v_add_f32_e32 v102, 1.0, v102
	v_add_f32_e32 v103, 1.0, v103
	v_add_f32_e32 v113, 1.0, v96
	v_add_f32_e32 v119, 1.0, v97
	v_add_f32_e32 v124, 1.0, v98
	v_add_f32_e32 v125, 1.0, v99
	v_rcp_f32_e32 v96, v100
	v_rcp_f32_e32 v97, v101
	v_rcp_f32_e32 v98, v102
	v_rcp_f32_e32 v99, v103
	v_rcp_f32_e32 v100, v113
	v_rcp_f32_e32 v101, v119
	v_rcp_f32_e32 v102, v124
	v_rcp_f32_e32 v103, v125
	v_pk_mul_f32 v[96:97], v[118:119], v[96:97] op_sel_hi:[0,1]
	v_pk_mul_f32 v[98:99], v[118:119], v[98:99] op_sel_hi:[0,1]
	v_pk_mul_f32 v[100:101], v[118:119], v[100:101] op_sel_hi:[0,1]
	v_pk_mul_f32 v[102:103], v[118:119], v[102:103] op_sel_hi:[0,1]
	v_pk_mul_f32 v[96:97], v[108:109], v[96:97]
	v_pk_mul_f32 v[98:99], v[110:111], v[98:99]
	v_pk_mul_f32 v[100:101], v[104:105], v[100:101]
	v_pk_mul_f32 v[102:103], v[106:107], v[102:103]
	v_cvt_pk_bf16_f32 v96, v96, v97
	v_cvt_pk_bf16_f32 v97, v98, v99
	v_cvt_pk_bf16_f32 v98, v100, v101
	v_cvt_pk_bf16_f32 v99, v102, v103
	global_store_dwordx4 v[114:115], v[96:99], off
	s_nop 1
	v_mov_b32_e32 v96, v192
	v_mov_b32_e32 v97, v193
	v_mov_b32_e32 v98, v194
	v_mov_b32_e32 v99, v195
	v_mov_b32_e32 v100, v97
	v_mov_b32_e32 v101, v98
	v_mov_b32_e32 v97, v99
	v_pk_add_f32 v[96:97], v[100:101], v[96:97]
	v_mad_i64_i32 v[98:99], s[0:1], v112, s49, v[150:151]
	v_add_f32_e32 v96, v96, v97
	ds_bpermute_b32 v97, v123, v96
	v_lshl_add_u64 v[98:99], v[98:99], 0, v[120:121]
	s_waitcnt lgkmcnt(0)
	v_add_f32_e32 v100, v96, v97
	ds_bpermute_b32 v101, v122, v100
	v_or_b32_e32 v96, 48, v152
	v_ashrrev_i32_e32 v97, 31, v96
	s_waitcnt lgkmcnt(0)
	v_add_f32_e32 v100, v100, v101
	v_fmamk_f32 v100, v100, 0x3a800000, v162
	v_mul_f32_e32 v101, 0x4b800000, v100
	v_cmp_gt_f32_e32 vcc, s52, v100
	s_nop 1
	v_cndmask_b32_e32 v100, v100, v101, vcc
	v_rsq_f32_e32 v102, v100
	v_lshlrev_b64 v[100:101], 6, v[96:97]
	v_lshl_add_u64 v[100:101], v[140:141], 0, v[100:101]
	v_mul_f32_e32 v97, 0x45800000, v102
	v_cndmask_b32_e32 v97, v102, v97, vcc
	v_mul_f32_e32 v103, 0xbfb8aa3b, v97
	v_mul_f32_e32 v84, v84, v103
	v_mul_f32_e32 v85, v85, v103
	v_mul_f32_e32 v86, v86, v103
	v_mul_f32_e32 v87, v87, v103
	v_mul_f32_e32 v80, v80, v103
	v_mul_f32_e32 v81, v81, v103
	v_mul_f32_e32 v82, v82, v103
	v_mul_f32_e32 v83, v83, v103
	v_exp_f32_e32 v84, v84
	v_exp_f32_e32 v85, v85
	v_exp_f32_e32 v86, v86
	v_exp_f32_e32 v87, v87
	v_exp_f32_e32 v80, v80
	v_exp_f32_e32 v81, v81
	v_exp_f32_e32 v82, v82
	v_exp_f32_e32 v83, v83
	v_mul_f32_e32 v102, v97, v97
	v_add_f32_e32 v84, 1.0, v84
	v_add_f32_e32 v85, 1.0, v85
	v_add_f32_e32 v86, 1.0, v86
	v_add_f32_e32 v87, 1.0, v87
	v_add_f32_e32 v97, 1.0, v80
	v_add_f32_e32 v103, 1.0, v81
	v_add_f32_e32 v104, 1.0, v82
	v_add_f32_e32 v105, 1.0, v83
	v_rcp_f32_e32 v80, v84
	v_rcp_f32_e32 v81, v85
	v_rcp_f32_e32 v82, v86
	v_rcp_f32_e32 v83, v87
	v_rcp_f32_e32 v84, v97
	v_rcp_f32_e32 v85, v103
	v_rcp_f32_e32 v86, v104
	v_rcp_f32_e32 v87, v105
	v_pk_mul_f32 v[80:81], v[102:103], v[80:81] op_sel_hi:[0,1]
	v_pk_mul_f32 v[82:83], v[102:103], v[82:83] op_sel_hi:[0,1]
	v_pk_mul_f32 v[84:85], v[102:103], v[84:85] op_sel_hi:[0,1]
	v_pk_mul_f32 v[86:87], v[102:103], v[86:87] op_sel_hi:[0,1]
	v_pk_mul_f32 v[80:81], v[92:93], v[80:81]
	v_pk_mul_f32 v[82:83], v[94:95], v[82:83]
	v_pk_mul_f32 v[84:85], v[88:89], v[84:85]
	v_pk_mul_f32 v[86:87], v[90:91], v[86:87]
	v_cvt_pk_bf16_f32 v80, v80, v81
	v_cvt_pk_bf16_f32 v81, v82, v83
	v_cvt_pk_bf16_f32 v82, v84, v85
	v_cvt_pk_bf16_f32 v83, v86, v87
	global_store_dwordx4 v[98:99], v[80:83], off
	s_nop 1
	v_mov_b32_e32 v80, v196
	v_mov_b32_e32 v81, v197
	v_mov_b32_e32 v82, v198
	v_mov_b32_e32 v83, v199
	v_mov_b32_e32 v84, v81
	v_mov_b32_e32 v85, v82
	v_mov_b32_e32 v81, v83
	v_pk_add_f32 v[80:81], v[84:85], v[80:81]
	v_mad_i64_i32 v[82:83], s[0:1], v96, s49, v[150:151]
	v_add_f32_e32 v80, v80, v81
	ds_bpermute_b32 v81, v123, v80
	v_lshl_add_u64 v[82:83], v[82:83], 0, v[120:121]
	s_waitcnt lgkmcnt(0)
	v_add_f32_e32 v84, v80, v81
	ds_bpermute_b32 v85, v122, v84
	v_add_u32_e32 v80, 0x80, v152
	v_ashrrev_i32_e32 v81, 31, v80
	s_waitcnt lgkmcnt(0)
	v_add_f32_e32 v84, v84, v85
	v_fmamk_f32 v84, v84, 0x3a800000, v162
	v_mul_f32_e32 v85, 0x4b800000, v84
	v_cmp_gt_f32_e32 vcc, s52, v84
	s_nop 1
	v_cndmask_b32_e32 v84, v84, v85, vcc
	v_rsq_f32_e32 v86, v84
	v_lshlrev_b64 v[84:85], 6, v[80:81]
	v_lshl_add_u64 v[84:85], v[140:141], 0, v[84:85]
	v_mul_f32_e32 v81, 0x45800000, v86
	v_cndmask_b32_e32 v81, v86, v81, vcc
	v_mul_f32_e32 v87, 0xbfb8aa3b, v81
	v_mul_f32_e32 v68, v68, v87
	v_mul_f32_e32 v69, v69, v87
	v_mul_f32_e32 v70, v70, v87
	v_mul_f32_e32 v71, v71, v87
	v_mul_f32_e32 v64, v64, v87
	v_mul_f32_e32 v65, v65, v87
	v_mul_f32_e32 v66, v66, v87
	v_mul_f32_e32 v67, v67, v87
	v_exp_f32_e32 v68, v68
	v_exp_f32_e32 v69, v69
	v_exp_f32_e32 v70, v70
	v_exp_f32_e32 v71, v71
	v_exp_f32_e32 v64, v64
	v_exp_f32_e32 v65, v65
	v_exp_f32_e32 v66, v66
	v_exp_f32_e32 v67, v67
	v_mul_f32_e32 v86, v81, v81
	v_add_f32_e32 v68, 1.0, v68
	v_add_f32_e32 v69, 1.0, v69
	v_add_f32_e32 v70, 1.0, v70
	v_add_f32_e32 v71, 1.0, v71
	v_add_f32_e32 v81, 1.0, v64
	v_add_f32_e32 v87, 1.0, v65
	v_add_f32_e32 v88, 1.0, v66
	v_add_f32_e32 v89, 1.0, v67
	v_rcp_f32_e32 v64, v68
	v_rcp_f32_e32 v65, v69
	v_rcp_f32_e32 v66, v70
	v_rcp_f32_e32 v67, v71
	v_rcp_f32_e32 v68, v81
	v_rcp_f32_e32 v69, v87
	v_rcp_f32_e32 v70, v88
	v_rcp_f32_e32 v71, v89
	v_pk_mul_f32 v[64:65], v[86:87], v[64:65] op_sel_hi:[0,1]
	v_pk_mul_f32 v[66:67], v[86:87], v[66:67] op_sel_hi:[0,1]
	v_pk_mul_f32 v[68:69], v[86:87], v[68:69] op_sel_hi:[0,1]
	v_pk_mul_f32 v[70:71], v[86:87], v[70:71] op_sel_hi:[0,1]
	v_pk_mul_f32 v[64:65], v[76:77], v[64:65]
	v_pk_mul_f32 v[66:67], v[78:79], v[66:67]
	v_pk_mul_f32 v[68:69], v[72:73], v[68:69]
	v_pk_mul_f32 v[70:71], v[74:75], v[70:71]
	v_cvt_pk_bf16_f32 v64, v64, v65
	v_cvt_pk_bf16_f32 v65, v66, v67
	v_cvt_pk_bf16_f32 v66, v68, v69
	v_cvt_pk_bf16_f32 v67, v70, v71
	global_store_dwordx4 v[82:83], v[64:67], off
	s_nop 1
	v_mov_b32_e32 v64, v200
	v_mov_b32_e32 v65, v201
	v_mov_b32_e32 v66, v202
	v_mov_b32_e32 v67, v203
	v_mov_b32_e32 v68, v65
	v_mov_b32_e32 v69, v66
	v_mov_b32_e32 v65, v67
	v_pk_add_f32 v[64:65], v[68:69], v[64:65]
	v_mad_i64_i32 v[66:67], s[0:1], v80, s49, v[150:151]
	v_add_f32_e32 v64, v64, v65
	ds_bpermute_b32 v65, v123, v64
	v_lshl_add_u64 v[66:67], v[66:67], 0, v[120:121]
	s_waitcnt lgkmcnt(0)
	v_add_f32_e32 v68, v64, v65
	ds_bpermute_b32 v69, v122, v68
	v_add_u32_e32 v64, 0x90, v152
	v_ashrrev_i32_e32 v65, 31, v64
	s_waitcnt lgkmcnt(0)
	v_add_f32_e32 v68, v68, v69
	v_fmamk_f32 v68, v68, 0x3a800000, v162
	v_mul_f32_e32 v69, 0x4b800000, v68
	v_cmp_gt_f32_e32 vcc, s52, v68
	s_nop 1
	v_cndmask_b32_e32 v68, v68, v69, vcc
	v_rsq_f32_e32 v70, v68
	v_lshlrev_b64 v[68:69], 6, v[64:65]
	v_lshl_add_u64 v[68:69], v[140:141], 0, v[68:69]
	v_mul_f32_e32 v65, 0x45800000, v70
	v_cndmask_b32_e32 v65, v70, v65, vcc
	v_mul_f32_e32 v71, 0xbfb8aa3b, v65
	v_mul_f32_e32 v52, v52, v71
	v_mul_f32_e32 v53, v53, v71
	v_mul_f32_e32 v54, v54, v71
	v_mul_f32_e32 v55, v55, v71
	v_mul_f32_e32 v48, v48, v71
	v_mul_f32_e32 v49, v49, v71
	v_mul_f32_e32 v50, v50, v71
	v_mul_f32_e32 v51, v51, v71
	v_exp_f32_e32 v52, v52
	v_exp_f32_e32 v53, v53
	v_exp_f32_e32 v54, v54
	v_exp_f32_e32 v55, v55
	v_exp_f32_e32 v48, v48
	v_exp_f32_e32 v49, v49
	v_exp_f32_e32 v50, v50
	v_exp_f32_e32 v51, v51
	v_mul_f32_e32 v70, v65, v65
	v_add_f32_e32 v52, 1.0, v52
	v_add_f32_e32 v53, 1.0, v53
	v_add_f32_e32 v54, 1.0, v54
	v_add_f32_e32 v55, 1.0, v55
	v_add_f32_e32 v65, 1.0, v48
	v_add_f32_e32 v71, 1.0, v49
	v_add_f32_e32 v72, 1.0, v50
	v_add_f32_e32 v73, 1.0, v51
	v_rcp_f32_e32 v48, v52
	v_rcp_f32_e32 v49, v53
	v_rcp_f32_e32 v50, v54
	v_rcp_f32_e32 v51, v55
	v_rcp_f32_e32 v52, v65
	v_rcp_f32_e32 v53, v71
	v_rcp_f32_e32 v54, v72
	v_rcp_f32_e32 v55, v73
	v_pk_mul_f32 v[48:49], v[70:71], v[48:49] op_sel_hi:[0,1]
	v_pk_mul_f32 v[50:51], v[70:71], v[50:51] op_sel_hi:[0,1]
	v_pk_mul_f32 v[52:53], v[70:71], v[52:53] op_sel_hi:[0,1]
	v_pk_mul_f32 v[54:55], v[70:71], v[54:55] op_sel_hi:[0,1]
	v_pk_mul_f32 v[48:49], v[60:61], v[48:49]
	v_pk_mul_f32 v[50:51], v[62:63], v[50:51]
	v_pk_mul_f32 v[52:53], v[56:57], v[52:53]
	v_pk_mul_f32 v[54:55], v[58:59], v[54:55]
	v_cvt_pk_bf16_f32 v48, v48, v49
	v_cvt_pk_bf16_f32 v49, v50, v51
	v_cvt_pk_bf16_f32 v50, v52, v53
	v_cvt_pk_bf16_f32 v51, v54, v55
	global_store_dwordx4 v[66:67], v[48:51], off
	s_nop 1
	v_mov_b32_e32 v48, v204
	v_mov_b32_e32 v49, v205
	v_mov_b32_e32 v50, v206
	v_mov_b32_e32 v51, v207
	v_mov_b32_e32 v52, v49
	v_mov_b32_e32 v53, v50
	v_mov_b32_e32 v49, v51
	v_pk_add_f32 v[48:49], v[52:53], v[48:49]
	v_mad_i64_i32 v[50:51], s[0:1], v64, s49, v[150:151]
	v_add_f32_e32 v48, v48, v49
	ds_bpermute_b32 v49, v123, v48
	v_lshl_add_u64 v[50:51], v[50:51], 0, v[120:121]
	s_waitcnt lgkmcnt(0)
	v_add_f32_e32 v52, v48, v49
	ds_bpermute_b32 v53, v122, v52
	v_add_u32_e32 v48, 0xa0, v152
	v_ashrrev_i32_e32 v49, 31, v48
	s_waitcnt lgkmcnt(0)
	v_add_f32_e32 v52, v52, v53
	v_fmamk_f32 v52, v52, 0x3a800000, v162
	v_mul_f32_e32 v53, 0x4b800000, v52
	v_cmp_gt_f32_e32 vcc, s52, v52
	s_nop 1
	v_cndmask_b32_e32 v52, v52, v53, vcc
	v_rsq_f32_e32 v54, v52
	v_lshlrev_b64 v[52:53], 6, v[48:49]
	v_lshl_add_u64 v[52:53], v[140:141], 0, v[52:53]
	v_mul_f32_e32 v49, 0x45800000, v54
	v_cndmask_b32_e32 v49, v54, v49, vcc
	v_mul_f32_e32 v55, 0xbfb8aa3b, v49
	v_mul_f32_e32 v36, v36, v55
	v_mul_f32_e32 v37, v37, v55
	v_mul_f32_e32 v38, v38, v55
	v_mul_f32_e32 v39, v39, v55
	v_mul_f32_e32 v32, v32, v55
	v_mul_f32_e32 v33, v33, v55
	v_mul_f32_e32 v34, v34, v55
	v_mul_f32_e32 v35, v35, v55
	v_exp_f32_e32 v36, v36
	v_exp_f32_e32 v37, v37
	v_exp_f32_e32 v38, v38
	v_exp_f32_e32 v39, v39
	v_exp_f32_e32 v32, v32
	v_exp_f32_e32 v33, v33
	v_exp_f32_e32 v34, v34
	v_exp_f32_e32 v35, v35
	v_mul_f32_e32 v54, v49, v49
	v_add_f32_e32 v36, 1.0, v36
	v_add_f32_e32 v37, 1.0, v37
	v_add_f32_e32 v38, 1.0, v38
	v_add_f32_e32 v39, 1.0, v39
	v_add_f32_e32 v49, 1.0, v32
	v_add_f32_e32 v55, 1.0, v33
	v_add_f32_e32 v56, 1.0, v34
	v_add_f32_e32 v57, 1.0, v35
	v_rcp_f32_e32 v32, v36
	v_rcp_f32_e32 v33, v37
	v_rcp_f32_e32 v34, v38
	v_rcp_f32_e32 v35, v39
	v_rcp_f32_e32 v36, v49
	v_rcp_f32_e32 v37, v55
	v_rcp_f32_e32 v38, v56
	v_rcp_f32_e32 v39, v57
	v_pk_mul_f32 v[32:33], v[54:55], v[32:33] op_sel_hi:[0,1]
	v_pk_mul_f32 v[34:35], v[54:55], v[34:35] op_sel_hi:[0,1]
	v_pk_mul_f32 v[36:37], v[54:55], v[36:37] op_sel_hi:[0,1]
	v_pk_mul_f32 v[38:39], v[54:55], v[38:39] op_sel_hi:[0,1]
	v_pk_mul_f32 v[32:33], v[44:45], v[32:33]
	v_pk_mul_f32 v[34:35], v[46:47], v[34:35]
	v_pk_mul_f32 v[36:37], v[40:41], v[36:37]
	v_pk_mul_f32 v[38:39], v[42:43], v[38:39]
	v_cvt_pk_bf16_f32 v32, v32, v33
	v_cvt_pk_bf16_f32 v33, v34, v35
	v_cvt_pk_bf16_f32 v34, v36, v37
	v_cvt_pk_bf16_f32 v35, v38, v39
	global_store_dwordx4 v[50:51], v[32:35], off
	s_nop 1
	v_mov_b32_e32 v32, v208
	v_mov_b32_e32 v33, v209
	v_mov_b32_e32 v34, v210
	v_mov_b32_e32 v35, v211
	v_mov_b32_e32 v36, v33
	v_mov_b32_e32 v37, v34
	v_mov_b32_e32 v33, v35
	v_pk_add_f32 v[32:33], v[36:37], v[32:33]
	v_mad_i64_i32 v[34:35], s[0:1], v48, s49, v[150:151]
	v_add_f32_e32 v32, v32, v33
	ds_bpermute_b32 v33, v123, v32
	v_lshl_add_u64 v[34:35], v[34:35], 0, v[120:121]
	s_waitcnt lgkmcnt(0)
	v_add_f32_e32 v36, v32, v33
	ds_bpermute_b32 v37, v122, v36
	v_add_u32_e32 v32, 0xb0, v152
	v_ashrrev_i32_e32 v33, 31, v32
	s_waitcnt lgkmcnt(0)
	v_add_f32_e32 v36, v36, v37
	v_fmamk_f32 v36, v36, 0x3a800000, v162
	v_mul_f32_e32 v37, 0x4b800000, v36
	v_cmp_gt_f32_e32 vcc, s52, v36
	s_nop 1
	v_cndmask_b32_e32 v36, v36, v37, vcc
	v_rsq_f32_e32 v38, v36
	v_lshlrev_b64 v[36:37], 6, v[32:33]
	v_lshl_add_u64 v[36:37], v[140:141], 0, v[36:37]
	v_mul_f32_e32 v33, 0x45800000, v38
	v_cndmask_b32_e32 v33, v38, v33, vcc
	v_mul_f32_e32 v39, 0xbfb8aa3b, v33
	v_mul_f32_e32 v20, v20, v39
	v_mul_f32_e32 v21, v21, v39
	v_mul_f32_e32 v22, v22, v39
	v_mul_f32_e32 v23, v23, v39
	v_mul_f32_e32 v16, v16, v39
	v_mul_f32_e32 v17, v17, v39
	v_mul_f32_e32 v18, v18, v39
	v_mul_f32_e32 v19, v19, v39
	v_exp_f32_e32 v20, v20
	v_exp_f32_e32 v21, v21
	v_exp_f32_e32 v22, v22
	v_exp_f32_e32 v23, v23
	v_exp_f32_e32 v16, v16
	v_exp_f32_e32 v17, v17
	v_exp_f32_e32 v18, v18
	v_exp_f32_e32 v19, v19
	v_mul_f32_e32 v38, v33, v33
	v_add_f32_e32 v20, 1.0, v20
	v_add_f32_e32 v21, 1.0, v21
	v_add_f32_e32 v22, 1.0, v22
	v_add_f32_e32 v23, 1.0, v23
	v_add_f32_e32 v33, 1.0, v16
	v_add_f32_e32 v39, 1.0, v17
	v_add_f32_e32 v40, 1.0, v18
	v_add_f32_e32 v41, 1.0, v19
	v_rcp_f32_e32 v16, v20
	v_rcp_f32_e32 v17, v21
	v_rcp_f32_e32 v18, v22
	v_rcp_f32_e32 v19, v23
	v_rcp_f32_e32 v20, v33
	v_rcp_f32_e32 v21, v39
	v_rcp_f32_e32 v22, v40
	v_rcp_f32_e32 v23, v41
	v_pk_mul_f32 v[16:17], v[38:39], v[16:17] op_sel_hi:[0,1]
	v_pk_mul_f32 v[18:19], v[38:39], v[18:19] op_sel_hi:[0,1]
	v_pk_mul_f32 v[20:21], v[38:39], v[20:21] op_sel_hi:[0,1]
	v_pk_mul_f32 v[22:23], v[38:39], v[22:23] op_sel_hi:[0,1]
	v_pk_mul_f32 v[16:17], v[28:29], v[16:17]
	v_pk_mul_f32 v[18:19], v[30:31], v[18:19]
	v_pk_mul_f32 v[20:21], v[24:25], v[20:21]
	v_pk_mul_f32 v[22:23], v[26:27], v[22:23]
	v_cvt_pk_bf16_f32 v16, v16, v17
	v_cvt_pk_bf16_f32 v17, v18, v19
	v_cvt_pk_bf16_f32 v18, v20, v21
	v_cvt_pk_bf16_f32 v19, v22, v23
	global_store_dwordx4 v[34:35], v[16:19], off
	s_andn2_b64 vcc, exec, s[4:5]
	s_nop 1
	v_mov_b32_e32 v16, v212
	v_mov_b32_e32 v17, v213
	v_mov_b32_e32 v18, v214
	v_mov_b32_e32 v19, v215
	v_mov_b32_e32 v20, v17
	v_mov_b32_e32 v21, v18
	v_mov_b32_e32 v17, v19
	v_pk_add_f32 v[16:17], v[20:21], v[16:17]
	s_nop 0
	v_add_f32_e32 v16, v16, v17
	ds_bpermute_b32 v17, v123, v16
	s_waitcnt lgkmcnt(0)
	v_add_f32_e32 v16, v16, v17
	ds_bpermute_b32 v17, v122, v16
	s_waitcnt lgkmcnt(0)
	v_add_f32_e32 v16, v16, v17
	v_fmamk_f32 v16, v16, 0x3a800000, v162
	v_mul_f32_e32 v17, 0x4b800000, v16
	v_cmp_gt_f32_e64 s[0:1], s52, v16
	s_nop 1
	v_cndmask_b32_e64 v16, v16, v17, s[0:1]
	v_rsq_f32_e32 v18, v16
	v_mad_i64_i32 v[16:17], s[24:25], v32, s49, v[150:151]
	v_lshl_add_u64 v[16:17], v[16:17], 0, v[120:121]
	v_mul_f32_e32 v19, 0x45800000, v18
	v_cndmask_b32_e64 v18, v18, v19, s[0:1]
	v_mul_f32_e32 v19, 0xbfb8aa3b, v18
	v_mul_f32_e32 v4, v4, v19
	v_mul_f32_e32 v5, v5, v19
	v_mul_f32_e32 v6, v6, v19
	v_mul_f32_e32 v7, v7, v19
	v_mul_f32_e32 v0, v0, v19
	v_mul_f32_e32 v1, v1, v19
	v_mul_f32_e32 v2, v2, v19
	v_mul_f32_e32 v3, v3, v19
	v_exp_f32_e32 v4, v4
	v_exp_f32_e32 v5, v5
	v_exp_f32_e32 v6, v6
	v_exp_f32_e32 v7, v7
	v_exp_f32_e32 v0, v0
	v_exp_f32_e32 v1, v1
	v_exp_f32_e32 v2, v2
	v_exp_f32_e32 v3, v3
	v_add_f32_e32 v4, 1.0, v4
	v_add_f32_e32 v5, 1.0, v5
	v_add_f32_e32 v6, 1.0, v6
	v_add_f32_e32 v7, 1.0, v7
	v_add_f32_e32 v19, 1.0, v0
	v_add_f32_e32 v20, 1.0, v1
	v_add_f32_e32 v21, 1.0, v2
	v_add_f32_e32 v22, 1.0, v3
	v_rcp_f32_e32 v0, v4
	v_rcp_f32_e32 v1, v5
	v_rcp_f32_e32 v2, v6
	v_rcp_f32_e32 v3, v7
	v_rcp_f32_e32 v4, v19
	v_rcp_f32_e32 v5, v20
	v_rcp_f32_e32 v6, v21
	v_rcp_f32_e32 v7, v22
	v_mul_f32_e32 v18, v18, v18
	v_pk_mul_f32 v[0:1], v[18:19], v[0:1] op_sel_hi:[0,1]
	v_pk_mul_f32 v[2:3], v[18:19], v[2:3] op_sel_hi:[0,1]
	v_pk_mul_f32 v[4:5], v[18:19], v[4:5] op_sel_hi:[0,1]
	v_pk_mul_f32 v[6:7], v[18:19], v[6:7] op_sel_hi:[0,1]
	v_pk_mul_f32 v[0:1], v[12:13], v[0:1]
	v_pk_mul_f32 v[2:3], v[14:15], v[2:3]
	v_pk_mul_f32 v[4:5], v[8:9], v[4:5]
	v_pk_mul_f32 v[6:7], v[10:11], v[6:7]
	v_cvt_pk_bf16_f32 v0, v0, v1
	v_cvt_pk_bf16_f32 v1, v2, v3
	v_cvt_pk_bf16_f32 v2, v4, v5
	v_cvt_pk_bf16_f32 v3, v6, v7
	s_mov_b64 s[0:1], -1
	global_store_dwordx4 v[16:17], v[0:3], off
	s_cbranch_vccnz .LBB0_620
	s_andn2_b64 vcc, exec, s[8:9]
	s_cbranch_vccnz .LBB0_619
	s_barrier
	s_branch .LBB0_619

.LBB0_1238:
	v_lshl_add_u32 v152, s0, 8, v131
	v_ashrrev_i32_e32 v153, 31, v152
	v_lshlrev_b64 v[150:151], 6, v[152:153]
	v_lshl_add_u64 v[150:151], v[140:141], 0, v[150:151]
	global_load_dwordx4 v[162:165], v[150:151], off
	global_load_dwordx4 v[188:191], v[150:151], off offset:1024
	global_load_dwordx4 v[192:195], v[150:151], off offset:2048
	global_load_dwordx4 v[196:199], v[150:151], off offset:3072
	v_mov_b32_e32 v216, 0x2000
	v_mov_b32_e32 v217, 0
	v_lshl_add_u64 v[216:217], v[150:151], 0, v[216:217]
	global_load_dwordx4 v[200:203], v[216:217], off
	global_load_dwordx4 v[204:207], v[216:217], off offset:1024
	global_load_dwordx4 v[208:211], v[216:217], off offset:2048
	global_load_dwordx4 v[212:215], v[216:217], off offset:3072
	v_and_b32_e32 v161, 64, v159
	v_xor_b32_e32 v153, 16, v159
	v_pk_mul_f32 v[168:169], v[114:115], v[122:123]
	v_add_u32_e32 v122, 64, v161
	v_cmp_lt_i32_e32 vcc, v153, v122
	v_pk_mul_f32 v[170:171], v[112:113], v[120:121]
	v_xor_b32_e32 v172, 32, v159
	v_cndmask_b32_e32 v120, v159, v153, vcc
	v_lshlrev_b32_e32 v123, 2, v120
	v_cmp_lt_i32_e32 vcc, v172, v122
	v_pk_mul_f32 v[126:127], v[118:119], v[126:127]
	v_pk_mul_f32 v[124:125], v[116:117], v[124:125]
	v_cndmask_b32_e32 v122, v159, v172, vcc
	v_lshlrev_b32_e32 v122, 2, v122
	v_lshl_or_b32 v166, s1, 7, v155
	v_ashrrev_i32_e32 v167, 31, v166
	v_mov_b64_e32 v[150:151], s[10:11]
	v_pk_mul_f32 v[110:111], v[102:103], v[110:111]
	v_pk_mul_f32 v[108:109], v[100:101], v[108:109]
	v_pk_mul_f32 v[106:107], v[98:99], v[106:107]
	v_pk_mul_f32 v[104:105], v[96:97], v[104:105]
	v_pk_mul_f32 v[94:95], v[86:87], v[94:95]
	v_pk_mul_f32 v[92:93], v[84:85], v[92:93]
	v_pk_mul_f32 v[90:91], v[82:83], v[90:91]
	v_pk_mul_f32 v[88:89], v[80:81], v[88:89]
	v_pk_mul_f32 v[78:79], v[70:71], v[78:79]
	v_pk_mul_f32 v[76:77], v[68:69], v[76:77]
	v_pk_mul_f32 v[74:75], v[66:67], v[74:75]
	v_pk_mul_f32 v[72:73], v[64:65], v[72:73]
	v_pk_mul_f32 v[62:63], v[54:55], v[62:63]
	v_pk_mul_f32 v[60:61], v[52:53], v[60:61]
	v_pk_mul_f32 v[58:59], v[50:51], v[58:59]
	v_pk_mul_f32 v[56:57], v[48:49], v[56:57]
	v_pk_mul_f32 v[46:47], v[38:39], v[46:47]
	v_pk_mul_f32 v[44:45], v[36:37], v[44:45]
	v_pk_mul_f32 v[42:43], v[34:35], v[42:43]
	v_pk_mul_f32 v[40:41], v[32:33], v[40:41]
	v_pk_mul_f32 v[30:31], v[22:23], v[30:31]
	v_pk_mul_f32 v[28:29], v[20:21], v[28:29]
	v_pk_mul_f32 v[26:27], v[18:19], v[26:27]
	v_pk_mul_f32 v[24:25], v[16:17], v[24:25]
	v_pk_mul_f32 v[14:15], v[6:7], v[14:15]
	v_pk_mul_f32 v[12:13], v[4:5], v[12:13]
	v_pk_mul_f32 v[10:11], v[2:3], v[10:11]
	v_pk_mul_f32 v[8:9], v[0:1], v[8:9]
	s_waitcnt vmcnt(0)
	v_mov_b32_e32 v120, v163
	v_mov_b32_e32 v121, v164
	v_mov_b32_e32 v163, v165
	v_pk_add_f32 v[120:121], v[120:121], v[162:163]
	v_or_b32_e32 v164, 16, v152
	v_add_f32_e32 v120, v120, v121
	ds_bpermute_b32 v121, v123, v120
	v_ashrrev_i32_e32 v165, 31, v164
	v_mad_i64_i32 v[162:163], s[0:1], v152, s49, v[150:151]
	s_waitcnt lgkmcnt(0)
	v_add_f32_e32 v153, v120, v121
	ds_bpermute_b32 v161, v122, v153
	v_lshlrev_b64 v[120:121], 1, v[166:167]
	v_lshlrev_b64 v[166:167], 6, v[164:165]
	v_lshl_add_u64 v[162:163], v[162:163], 0, v[120:121]
	v_lshl_add_u64 v[166:167], v[140:141], 0, v[166:167]
	s_waitcnt lgkmcnt(0)
	v_add_f32_e32 v153, v153, v161
	v_fmamk_f32 v153, v153, 0x3a800000, v160
	v_mul_f32_e32 v161, 0x4b800000, v153
	v_cmp_gt_f32_e32 vcc, s52, v153
	s_nop 1
	v_cndmask_b32_e32 v153, v153, v161, vcc
	v_rsq_f32_e32 v153, v153
	s_nop 0
	v_mul_f32_e32 v161, 0x45800000, v153
	v_cndmask_b32_e32 v153, v153, v161, vcc
	v_mul_f32_e32 v161, 0xbfb8aa3b, v153
	v_mul_f32_e32 v116, v116, v161
	v_mul_f32_e32 v117, v117, v161
	v_mul_f32_e32 v118, v118, v161
	v_mul_f32_e32 v119, v119, v161
	v_mul_f32_e32 v112, v112, v161
	v_mul_f32_e32 v113, v113, v161
	v_mul_f32_e32 v114, v114, v161
	v_mul_f32_e32 v115, v115, v161
	v_exp_f32_e32 v116, v116
	v_exp_f32_e32 v117, v117
	v_exp_f32_e32 v118, v118
	v_exp_f32_e32 v119, v119
	v_exp_f32_e32 v112, v112
	v_exp_f32_e32 v113, v113
	v_exp_f32_e32 v114, v114
	v_exp_f32_e32 v115, v115
	v_mul_f32_e32 v172, v153, v153
	v_add_f32_e32 v116, 1.0, v116
	v_add_f32_e32 v117, 1.0, v117
	v_add_f32_e32 v118, 1.0, v118
	v_add_f32_e32 v119, 1.0, v119
	v_add_f32_e32 v153, 1.0, v112
	v_add_f32_e32 v161, 1.0, v113
	v_add_f32_e32 v165, 1.0, v114
	v_add_f32_e32 v173, 1.0, v115
	v_rcp_f32_e32 v112, v116
	v_rcp_f32_e32 v113, v117
	v_rcp_f32_e32 v114, v118
	v_rcp_f32_e32 v115, v119
	v_rcp_f32_e32 v116, v153
	v_rcp_f32_e32 v117, v161
	v_rcp_f32_e32 v118, v165
	v_rcp_f32_e32 v119, v173
	v_pk_mul_f32 v[112:113], v[172:173], v[112:113] op_sel_hi:[0,1]
	v_pk_mul_f32 v[114:115], v[172:173], v[114:115] op_sel_hi:[0,1]
	v_pk_mul_f32 v[116:117], v[172:173], v[116:117] op_sel_hi:[0,1]
	v_pk_mul_f32 v[118:119], v[172:173], v[118:119] op_sel_hi:[0,1]
	v_pk_mul_f32 v[112:113], v[124:125], v[112:113]
	v_pk_mul_f32 v[114:115], v[126:127], v[114:115]
	v_pk_mul_f32 v[116:117], v[170:171], v[116:117]
	v_pk_mul_f32 v[118:119], v[168:169], v[118:119]
	v_cvt_pk_bf16_f32 v112, v112, v113
	v_cvt_pk_bf16_f32 v113, v114, v115
	v_cvt_pk_bf16_f32 v114, v116, v117
	v_cvt_pk_bf16_f32 v115, v118, v119
	global_store_dwordx4 v[162:163], v[112:115], off
	s_nop 1
	v_mov_b32_e32 v112, v188
	v_mov_b32_e32 v113, v189
	v_mov_b32_e32 v114, v190
	v_mov_b32_e32 v115, v191
	v_mov_b32_e32 v116, v113
	v_mov_b32_e32 v117, v114
	v_mov_b32_e32 v113, v115
	v_pk_add_f32 v[112:113], v[116:117], v[112:113]
	v_mad_i64_i32 v[114:115], s[0:1], v164, s49, v[150:151]
	v_add_f32_e32 v112, v112, v113
	ds_bpermute_b32 v113, v123, v112
	v_lshl_add_u64 v[114:115], v[114:115], 0, v[120:121]
	s_waitcnt lgkmcnt(0)
	v_add_f32_e32 v116, v112, v113
	ds_bpermute_b32 v117, v122, v116
	v_or_b32_e32 v112, 32, v152
	v_ashrrev_i32_e32 v113, 31, v112
	s_waitcnt lgkmcnt(0)
	v_add_f32_e32 v116, v116, v117
	v_fmamk_f32 v116, v116, 0x3a800000, v160
	v_mul_f32_e32 v117, 0x4b800000, v116
	v_cmp_gt_f32_e32 vcc, s52, v116
	s_nop 1
	v_cndmask_b32_e32 v116, v116, v117, vcc
	v_rsq_f32_e32 v118, v116
	v_lshlrev_b64 v[116:117], 6, v[112:113]
	v_lshl_add_u64 v[116:117], v[140:141], 0, v[116:117]
	v_mul_f32_e32 v113, 0x45800000, v118
	v_cndmask_b32_e32 v113, v118, v113, vcc
	v_mul_f32_e32 v119, 0xbfb8aa3b, v113
	v_mul_f32_e32 v100, v100, v119
	v_mul_f32_e32 v101, v101, v119
	v_mul_f32_e32 v102, v102, v119
	v_mul_f32_e32 v103, v103, v119
	v_mul_f32_e32 v96, v96, v119
	v_mul_f32_e32 v97, v97, v119
	v_mul_f32_e32 v98, v98, v119
	v_mul_f32_e32 v99, v99, v119
	v_exp_f32_e32 v100, v100
	v_exp_f32_e32 v101, v101
	v_exp_f32_e32 v102, v102
	v_exp_f32_e32 v103, v103
	v_exp_f32_e32 v96, v96
	v_exp_f32_e32 v97, v97
	v_exp_f32_e32 v98, v98
	v_exp_f32_e32 v99, v99
	v_mul_f32_e32 v118, v113, v113
	v_add_f32_e32 v100, 1.0, v100
	v_add_f32_e32 v101, 1.0, v101
	v_add_f32_e32 v102, 1.0, v102
	v_add_f32_e32 v103, 1.0, v103
	v_add_f32_e32 v113, 1.0, v96
	v_add_f32_e32 v119, 1.0, v97
	v_add_f32_e32 v124, 1.0, v98
	v_add_f32_e32 v125, 1.0, v99
	v_rcp_f32_e32 v96, v100
	v_rcp_f32_e32 v97, v101
	v_rcp_f32_e32 v98, v102
	v_rcp_f32_e32 v99, v103
	v_rcp_f32_e32 v100, v113
	v_rcp_f32_e32 v101, v119
	v_rcp_f32_e32 v102, v124
	v_rcp_f32_e32 v103, v125
	v_pk_mul_f32 v[96:97], v[118:119], v[96:97] op_sel_hi:[0,1]
	v_pk_mul_f32 v[98:99], v[118:119], v[98:99] op_sel_hi:[0,1]
	v_pk_mul_f32 v[100:101], v[118:119], v[100:101] op_sel_hi:[0,1]
	v_pk_mul_f32 v[102:103], v[118:119], v[102:103] op_sel_hi:[0,1]
	v_pk_mul_f32 v[96:97], v[108:109], v[96:97]
	v_pk_mul_f32 v[98:99], v[110:111], v[98:99]
	v_pk_mul_f32 v[100:101], v[104:105], v[100:101]
	v_pk_mul_f32 v[102:103], v[106:107], v[102:103]
	v_cvt_pk_bf16_f32 v96, v96, v97
	v_cvt_pk_bf16_f32 v97, v98, v99
	v_cvt_pk_bf16_f32 v98, v100, v101
	v_cvt_pk_bf16_f32 v99, v102, v103
	global_store_dwordx4 v[114:115], v[96:99], off
	s_nop 1
	v_mov_b32_e32 v96, v192
	v_mov_b32_e32 v97, v193
	v_mov_b32_e32 v98, v194
	v_mov_b32_e32 v99, v195
	v_mov_b32_e32 v100, v97
	v_mov_b32_e32 v101, v98
	v_mov_b32_e32 v97, v99
	v_pk_add_f32 v[96:97], v[100:101], v[96:97]
	v_mad_i64_i32 v[98:99], s[0:1], v112, s49, v[150:151]
	v_add_f32_e32 v96, v96, v97
	ds_bpermute_b32 v97, v123, v96
	v_lshl_add_u64 v[98:99], v[98:99], 0, v[120:121]
	s_waitcnt lgkmcnt(0)
	v_add_f32_e32 v100, v96, v97
	ds_bpermute_b32 v101, v122, v100
	v_or_b32_e32 v96, 48, v152
	v_ashrrev_i32_e32 v97, 31, v96
	s_waitcnt lgkmcnt(0)
	v_add_f32_e32 v100, v100, v101
	v_fmamk_f32 v100, v100, 0x3a800000, v160
	v_mul_f32_e32 v101, 0x4b800000, v100
	v_cmp_gt_f32_e32 vcc, s52, v100
	s_nop 1
	v_cndmask_b32_e32 v100, v100, v101, vcc
	v_rsq_f32_e32 v102, v100
	v_lshlrev_b64 v[100:101], 6, v[96:97]
	v_lshl_add_u64 v[100:101], v[140:141], 0, v[100:101]
	v_mul_f32_e32 v97, 0x45800000, v102
	v_cndmask_b32_e32 v97, v102, v97, vcc
	v_mul_f32_e32 v103, 0xbfb8aa3b, v97
	v_mul_f32_e32 v84, v84, v103
	v_mul_f32_e32 v85, v85, v103
	v_mul_f32_e32 v86, v86, v103
	v_mul_f32_e32 v87, v87, v103
	v_mul_f32_e32 v80, v80, v103
	v_mul_f32_e32 v81, v81, v103
	v_mul_f32_e32 v82, v82, v103
	v_mul_f32_e32 v83, v83, v103
	v_exp_f32_e32 v84, v84
	v_exp_f32_e32 v85, v85
	v_exp_f32_e32 v86, v86
	v_exp_f32_e32 v87, v87
	v_exp_f32_e32 v80, v80
	v_exp_f32_e32 v81, v81
	v_exp_f32_e32 v82, v82
	v_exp_f32_e32 v83, v83
	v_mul_f32_e32 v102, v97, v97
	v_add_f32_e32 v84, 1.0, v84
	v_add_f32_e32 v85, 1.0, v85
	v_add_f32_e32 v86, 1.0, v86
	v_add_f32_e32 v87, 1.0, v87
	v_add_f32_e32 v97, 1.0, v80
	v_add_f32_e32 v103, 1.0, v81
	v_add_f32_e32 v104, 1.0, v82
	v_add_f32_e32 v105, 1.0, v83
	v_rcp_f32_e32 v80, v84
	v_rcp_f32_e32 v81, v85
	v_rcp_f32_e32 v82, v86
	v_rcp_f32_e32 v83, v87
	v_rcp_f32_e32 v84, v97
	v_rcp_f32_e32 v85, v103
	v_rcp_f32_e32 v86, v104
	v_rcp_f32_e32 v87, v105
	v_pk_mul_f32 v[80:81], v[102:103], v[80:81] op_sel_hi:[0,1]
	v_pk_mul_f32 v[82:83], v[102:103], v[82:83] op_sel_hi:[0,1]
	v_pk_mul_f32 v[84:85], v[102:103], v[84:85] op_sel_hi:[0,1]
	v_pk_mul_f32 v[86:87], v[102:103], v[86:87] op_sel_hi:[0,1]
	v_pk_mul_f32 v[80:81], v[92:93], v[80:81]
	v_pk_mul_f32 v[82:83], v[94:95], v[82:83]
	v_pk_mul_f32 v[84:85], v[88:89], v[84:85]
	v_pk_mul_f32 v[86:87], v[90:91], v[86:87]
	v_cvt_pk_bf16_f32 v80, v80, v81
	v_cvt_pk_bf16_f32 v81, v82, v83
	v_cvt_pk_bf16_f32 v82, v84, v85
	v_cvt_pk_bf16_f32 v83, v86, v87
	global_store_dwordx4 v[98:99], v[80:83], off
	s_nop 1
	v_mov_b32_e32 v80, v196
	v_mov_b32_e32 v81, v197
	v_mov_b32_e32 v82, v198
	v_mov_b32_e32 v83, v199
	v_mov_b32_e32 v84, v81
	v_mov_b32_e32 v85, v82
	v_mov_b32_e32 v81, v83
	v_pk_add_f32 v[80:81], v[84:85], v[80:81]
	v_mad_i64_i32 v[82:83], s[0:1], v96, s49, v[150:151]
	v_add_f32_e32 v80, v80, v81
	ds_bpermute_b32 v81, v123, v80
	v_lshl_add_u64 v[82:83], v[82:83], 0, v[120:121]
	s_waitcnt lgkmcnt(0)
	v_add_f32_e32 v84, v80, v81
	ds_bpermute_b32 v85, v122, v84
	v_add_u32_e32 v80, 0x80, v152
	v_ashrrev_i32_e32 v81, 31, v80
	s_waitcnt lgkmcnt(0)
	v_add_f32_e32 v84, v84, v85
	v_fmamk_f32 v84, v84, 0x3a800000, v160
	v_mul_f32_e32 v85, 0x4b800000, v84
	v_cmp_gt_f32_e32 vcc, s52, v84
	s_nop 1
	v_cndmask_b32_e32 v84, v84, v85, vcc
	v_rsq_f32_e32 v86, v84
	v_lshlrev_b64 v[84:85], 6, v[80:81]
	v_lshl_add_u64 v[84:85], v[140:141], 0, v[84:85]
	v_mul_f32_e32 v81, 0x45800000, v86
	v_cndmask_b32_e32 v81, v86, v81, vcc
	v_mul_f32_e32 v87, 0xbfb8aa3b, v81
	v_mul_f32_e32 v68, v68, v87
	v_mul_f32_e32 v69, v69, v87
	v_mul_f32_e32 v70, v70, v87
	v_mul_f32_e32 v71, v71, v87
	v_mul_f32_e32 v64, v64, v87
	v_mul_f32_e32 v65, v65, v87
	v_mul_f32_e32 v66, v66, v87
	v_mul_f32_e32 v67, v67, v87
	v_exp_f32_e32 v68, v68
	v_exp_f32_e32 v69, v69
	v_exp_f32_e32 v70, v70
	v_exp_f32_e32 v71, v71
	v_exp_f32_e32 v64, v64
	v_exp_f32_e32 v65, v65
	v_exp_f32_e32 v66, v66
	v_exp_f32_e32 v67, v67
	v_mul_f32_e32 v86, v81, v81
	v_add_f32_e32 v68, 1.0, v68
	v_add_f32_e32 v69, 1.0, v69
	v_add_f32_e32 v70, 1.0, v70
	v_add_f32_e32 v71, 1.0, v71
	v_add_f32_e32 v81, 1.0, v64
	v_add_f32_e32 v87, 1.0, v65
	v_add_f32_e32 v88, 1.0, v66
	v_add_f32_e32 v89, 1.0, v67
	v_rcp_f32_e32 v64, v68
	v_rcp_f32_e32 v65, v69
	v_rcp_f32_e32 v66, v70
	v_rcp_f32_e32 v67, v71
	v_rcp_f32_e32 v68, v81
	v_rcp_f32_e32 v69, v87
	v_rcp_f32_e32 v70, v88
	v_rcp_f32_e32 v71, v89
	v_pk_mul_f32 v[64:65], v[86:87], v[64:65] op_sel_hi:[0,1]
	v_pk_mul_f32 v[66:67], v[86:87], v[66:67] op_sel_hi:[0,1]
	v_pk_mul_f32 v[68:69], v[86:87], v[68:69] op_sel_hi:[0,1]
	v_pk_mul_f32 v[70:71], v[86:87], v[70:71] op_sel_hi:[0,1]
	v_pk_mul_f32 v[64:65], v[76:77], v[64:65]
	v_pk_mul_f32 v[66:67], v[78:79], v[66:67]
	v_pk_mul_f32 v[68:69], v[72:73], v[68:69]
	v_pk_mul_f32 v[70:71], v[74:75], v[70:71]
	v_cvt_pk_bf16_f32 v64, v64, v65
	v_cvt_pk_bf16_f32 v65, v66, v67
	v_cvt_pk_bf16_f32 v66, v68, v69
	v_cvt_pk_bf16_f32 v67, v70, v71
	global_store_dwordx4 v[82:83], v[64:67], off
	s_nop 1
	v_mov_b32_e32 v64, v200
	v_mov_b32_e32 v65, v201
	v_mov_b32_e32 v66, v202
	v_mov_b32_e32 v67, v203
	v_mov_b32_e32 v68, v65
	v_mov_b32_e32 v69, v66
	v_mov_b32_e32 v65, v67
	v_pk_add_f32 v[64:65], v[68:69], v[64:65]
	v_mad_i64_i32 v[66:67], s[0:1], v80, s49, v[150:151]
	v_add_f32_e32 v64, v64, v65
	ds_bpermute_b32 v65, v123, v64
	v_lshl_add_u64 v[66:67], v[66:67], 0, v[120:121]
	s_waitcnt lgkmcnt(0)
	v_add_f32_e32 v68, v64, v65
	ds_bpermute_b32 v69, v122, v68
	v_add_u32_e32 v64, 0x90, v152
	v_ashrrev_i32_e32 v65, 31, v64
	s_waitcnt lgkmcnt(0)
	v_add_f32_e32 v68, v68, v69
	v_fmamk_f32 v68, v68, 0x3a800000, v160
	v_mul_f32_e32 v69, 0x4b800000, v68
	v_cmp_gt_f32_e32 vcc, s52, v68
	s_nop 1
	v_cndmask_b32_e32 v68, v68, v69, vcc
	v_rsq_f32_e32 v70, v68
	v_lshlrev_b64 v[68:69], 6, v[64:65]
	v_lshl_add_u64 v[68:69], v[140:141], 0, v[68:69]
	v_mul_f32_e32 v65, 0x45800000, v70
	v_cndmask_b32_e32 v65, v70, v65, vcc
	v_mul_f32_e32 v71, 0xbfb8aa3b, v65
	v_mul_f32_e32 v52, v52, v71
	v_mul_f32_e32 v53, v53, v71
	v_mul_f32_e32 v54, v54, v71
	v_mul_f32_e32 v55, v55, v71
	v_mul_f32_e32 v48, v48, v71
	v_mul_f32_e32 v49, v49, v71
	v_mul_f32_e32 v50, v50, v71
	v_mul_f32_e32 v51, v51, v71
	v_exp_f32_e32 v52, v52
	v_exp_f32_e32 v53, v53
	v_exp_f32_e32 v54, v54
	v_exp_f32_e32 v55, v55
	v_exp_f32_e32 v48, v48
	v_exp_f32_e32 v49, v49
	v_exp_f32_e32 v50, v50
	v_exp_f32_e32 v51, v51
	v_mul_f32_e32 v70, v65, v65
	v_add_f32_e32 v52, 1.0, v52
	v_add_f32_e32 v53, 1.0, v53
	v_add_f32_e32 v54, 1.0, v54
	v_add_f32_e32 v55, 1.0, v55
	v_add_f32_e32 v65, 1.0, v48
	v_add_f32_e32 v71, 1.0, v49
	v_add_f32_e32 v72, 1.0, v50
	v_add_f32_e32 v73, 1.0, v51
	v_rcp_f32_e32 v48, v52
	v_rcp_f32_e32 v49, v53
	v_rcp_f32_e32 v50, v54
	v_rcp_f32_e32 v51, v55
	v_rcp_f32_e32 v52, v65
	v_rcp_f32_e32 v53, v71
	v_rcp_f32_e32 v54, v72
	v_rcp_f32_e32 v55, v73
	v_pk_mul_f32 v[48:49], v[70:71], v[48:49] op_sel_hi:[0,1]
	v_pk_mul_f32 v[50:51], v[70:71], v[50:51] op_sel_hi:[0,1]
	v_pk_mul_f32 v[52:53], v[70:71], v[52:53] op_sel_hi:[0,1]
	v_pk_mul_f32 v[54:55], v[70:71], v[54:55] op_sel_hi:[0,1]
	v_pk_mul_f32 v[48:49], v[60:61], v[48:49]
	v_pk_mul_f32 v[50:51], v[62:63], v[50:51]
	v_pk_mul_f32 v[52:53], v[56:57], v[52:53]
	v_pk_mul_f32 v[54:55], v[58:59], v[54:55]
	v_cvt_pk_bf16_f32 v48, v48, v49
	v_cvt_pk_bf16_f32 v49, v50, v51
	v_cvt_pk_bf16_f32 v50, v52, v53
	v_cvt_pk_bf16_f32 v51, v54, v55
	global_store_dwordx4 v[66:67], v[48:51], off
	s_nop 1
	v_mov_b32_e32 v48, v204
	v_mov_b32_e32 v49, v205
	v_mov_b32_e32 v50, v206
	v_mov_b32_e32 v51, v207
	v_mov_b32_e32 v52, v49
	v_mov_b32_e32 v53, v50
	v_mov_b32_e32 v49, v51
	v_pk_add_f32 v[48:49], v[52:53], v[48:49]
	v_mad_i64_i32 v[50:51], s[0:1], v64, s49, v[150:151]
	v_add_f32_e32 v48, v48, v49
	ds_bpermute_b32 v49, v123, v48
	v_lshl_add_u64 v[50:51], v[50:51], 0, v[120:121]
	s_waitcnt lgkmcnt(0)
	v_add_f32_e32 v52, v48, v49
	ds_bpermute_b32 v53, v122, v52
	v_add_u32_e32 v48, 0xa0, v152
	v_ashrrev_i32_e32 v49, 31, v48
	s_waitcnt lgkmcnt(0)
	v_add_f32_e32 v52, v52, v53
	v_fmamk_f32 v52, v52, 0x3a800000, v160
	v_mul_f32_e32 v53, 0x4b800000, v52
	v_cmp_gt_f32_e32 vcc, s52, v52
	s_nop 1
	v_cndmask_b32_e32 v52, v52, v53, vcc
	v_rsq_f32_e32 v54, v52
	v_lshlrev_b64 v[52:53], 6, v[48:49]
	v_lshl_add_u64 v[52:53], v[140:141], 0, v[52:53]
	v_mul_f32_e32 v49, 0x45800000, v54
	v_cndmask_b32_e32 v49, v54, v49, vcc
	v_mul_f32_e32 v55, 0xbfb8aa3b, v49
	v_mul_f32_e32 v36, v36, v55
	v_mul_f32_e32 v37, v37, v55
	v_mul_f32_e32 v38, v38, v55
	v_mul_f32_e32 v39, v39, v55
	v_mul_f32_e32 v32, v32, v55
	v_mul_f32_e32 v33, v33, v55
	v_mul_f32_e32 v34, v34, v55
	v_mul_f32_e32 v35, v35, v55
	v_exp_f32_e32 v36, v36
	v_exp_f32_e32 v37, v37
	v_exp_f32_e32 v38, v38
	v_exp_f32_e32 v39, v39
	v_exp_f32_e32 v32, v32
	v_exp_f32_e32 v33, v33
	v_exp_f32_e32 v34, v34
	v_exp_f32_e32 v35, v35
	v_mul_f32_e32 v54, v49, v49
	v_add_f32_e32 v36, 1.0, v36
	v_add_f32_e32 v37, 1.0, v37
	v_add_f32_e32 v38, 1.0, v38
	v_add_f32_e32 v39, 1.0, v39
	v_add_f32_e32 v49, 1.0, v32
	v_add_f32_e32 v55, 1.0, v33
	v_add_f32_e32 v56, 1.0, v34
	v_add_f32_e32 v57, 1.0, v35
	v_rcp_f32_e32 v32, v36
	v_rcp_f32_e32 v33, v37
	v_rcp_f32_e32 v34, v38
	v_rcp_f32_e32 v35, v39
	v_rcp_f32_e32 v36, v49
	v_rcp_f32_e32 v37, v55
	v_rcp_f32_e32 v38, v56
	v_rcp_f32_e32 v39, v57
	v_pk_mul_f32 v[32:33], v[54:55], v[32:33] op_sel_hi:[0,1]
	v_pk_mul_f32 v[34:35], v[54:55], v[34:35] op_sel_hi:[0,1]
	v_pk_mul_f32 v[36:37], v[54:55], v[36:37] op_sel_hi:[0,1]
	v_pk_mul_f32 v[38:39], v[54:55], v[38:39] op_sel_hi:[0,1]
	v_pk_mul_f32 v[32:33], v[44:45], v[32:33]
	v_pk_mul_f32 v[34:35], v[46:47], v[34:35]
	v_pk_mul_f32 v[36:37], v[40:41], v[36:37]
	v_pk_mul_f32 v[38:39], v[42:43], v[38:39]
	v_cvt_pk_bf16_f32 v32, v32, v33
	v_cvt_pk_bf16_f32 v33, v34, v35
	v_cvt_pk_bf16_f32 v34, v36, v37
	v_cvt_pk_bf16_f32 v35, v38, v39
	global_store_dwordx4 v[50:51], v[32:35], off
	s_nop 1
	v_mov_b32_e32 v32, v208
	v_mov_b32_e32 v33, v209
	v_mov_b32_e32 v34, v210
	v_mov_b32_e32 v35, v211
	v_mov_b32_e32 v36, v33
	v_mov_b32_e32 v37, v34
	v_mov_b32_e32 v33, v35
	v_pk_add_f32 v[32:33], v[36:37], v[32:33]
	v_mad_i64_i32 v[34:35], s[0:1], v48, s49, v[150:151]
	v_add_f32_e32 v32, v32, v33
	ds_bpermute_b32 v33, v123, v32
	v_lshl_add_u64 v[34:35], v[34:35], 0, v[120:121]
	s_waitcnt lgkmcnt(0)
	v_add_f32_e32 v36, v32, v33
	ds_bpermute_b32 v37, v122, v36
	v_add_u32_e32 v32, 0xb0, v152
	v_ashrrev_i32_e32 v33, 31, v32
	s_waitcnt lgkmcnt(0)
	v_add_f32_e32 v36, v36, v37
	v_fmamk_f32 v36, v36, 0x3a800000, v160
	v_mul_f32_e32 v37, 0x4b800000, v36
	v_cmp_gt_f32_e32 vcc, s52, v36
	s_nop 1
	v_cndmask_b32_e32 v36, v36, v37, vcc
	v_rsq_f32_e32 v38, v36
	v_lshlrev_b64 v[36:37], 6, v[32:33]
	v_lshl_add_u64 v[36:37], v[140:141], 0, v[36:37]
	v_mul_f32_e32 v33, 0x45800000, v38
	v_cndmask_b32_e32 v33, v38, v33, vcc
	v_mul_f32_e32 v39, 0xbfb8aa3b, v33
	v_mul_f32_e32 v20, v20, v39
	v_mul_f32_e32 v21, v21, v39
	v_mul_f32_e32 v22, v22, v39
	v_mul_f32_e32 v23, v23, v39
	v_mul_f32_e32 v16, v16, v39
	v_mul_f32_e32 v17, v17, v39
	v_mul_f32_e32 v18, v18, v39
	v_mul_f32_e32 v19, v19, v39
	v_exp_f32_e32 v20, v20
	v_exp_f32_e32 v21, v21
	v_exp_f32_e32 v22, v22
	v_exp_f32_e32 v23, v23
	v_exp_f32_e32 v16, v16
	v_exp_f32_e32 v17, v17
	v_exp_f32_e32 v18, v18
	v_exp_f32_e32 v19, v19
	v_mul_f32_e32 v38, v33, v33
	v_add_f32_e32 v20, 1.0, v20
	v_add_f32_e32 v21, 1.0, v21
	v_add_f32_e32 v22, 1.0, v22
	v_add_f32_e32 v23, 1.0, v23
	v_add_f32_e32 v33, 1.0, v16
	v_add_f32_e32 v39, 1.0, v17
	v_add_f32_e32 v40, 1.0, v18
	v_add_f32_e32 v41, 1.0, v19
	v_rcp_f32_e32 v16, v20
	v_rcp_f32_e32 v17, v21
	v_rcp_f32_e32 v18, v22
	v_rcp_f32_e32 v19, v23
	v_rcp_f32_e32 v20, v33
	v_rcp_f32_e32 v21, v39
	v_rcp_f32_e32 v22, v40
	v_rcp_f32_e32 v23, v41
	v_pk_mul_f32 v[16:17], v[38:39], v[16:17] op_sel_hi:[0,1]
	v_pk_mul_f32 v[18:19], v[38:39], v[18:19] op_sel_hi:[0,1]
	v_pk_mul_f32 v[20:21], v[38:39], v[20:21] op_sel_hi:[0,1]
	v_pk_mul_f32 v[22:23], v[38:39], v[22:23] op_sel_hi:[0,1]
	v_pk_mul_f32 v[16:17], v[28:29], v[16:17]
	v_pk_mul_f32 v[18:19], v[30:31], v[18:19]
	v_pk_mul_f32 v[20:21], v[24:25], v[20:21]
	v_pk_mul_f32 v[22:23], v[26:27], v[22:23]
	v_cvt_pk_bf16_f32 v16, v16, v17
	v_cvt_pk_bf16_f32 v17, v18, v19
	v_cvt_pk_bf16_f32 v18, v20, v21
	v_cvt_pk_bf16_f32 v19, v22, v23
	global_store_dwordx4 v[34:35], v[16:19], off
	s_andn2_b64 vcc, exec, s[4:5]
	s_nop 1
	v_mov_b32_e32 v16, v212
	v_mov_b32_e32 v17, v213
	v_mov_b32_e32 v18, v214
	v_mov_b32_e32 v19, v215
	v_mov_b32_e32 v20, v17
	v_mov_b32_e32 v21, v18
	v_mov_b32_e32 v17, v19
	v_pk_add_f32 v[16:17], v[20:21], v[16:17]
	s_nop 0
	v_add_f32_e32 v16, v16, v17
	ds_bpermute_b32 v17, v123, v16
	s_waitcnt lgkmcnt(0)
	v_add_f32_e32 v16, v16, v17
	ds_bpermute_b32 v17, v122, v16
	s_waitcnt lgkmcnt(0)
	v_add_f32_e32 v16, v16, v17
	v_fmamk_f32 v16, v16, 0x3a800000, v160
	v_mul_f32_e32 v17, 0x4b800000, v16
	v_cmp_gt_f32_e64 s[0:1], s52, v16
	s_nop 1
	v_cndmask_b32_e64 v16, v16, v17, s[0:1]
	v_rsq_f32_e32 v18, v16
	v_mad_i64_i32 v[16:17], s[24:25], v32, s49, v[150:151]
	v_lshl_add_u64 v[16:17], v[16:17], 0, v[120:121]
	v_mul_f32_e32 v19, 0x45800000, v18
	v_cndmask_b32_e64 v18, v18, v19, s[0:1]
	v_mul_f32_e32 v19, 0xbfb8aa3b, v18
	v_mul_f32_e32 v4, v4, v19
	v_mul_f32_e32 v5, v5, v19
	v_mul_f32_e32 v6, v6, v19
	v_mul_f32_e32 v7, v7, v19
	v_mul_f32_e32 v0, v0, v19
	v_mul_f32_e32 v1, v1, v19
	v_mul_f32_e32 v2, v2, v19
	v_mul_f32_e32 v3, v3, v19
	v_exp_f32_e32 v4, v4
	v_exp_f32_e32 v5, v5
	v_exp_f32_e32 v6, v6
	v_exp_f32_e32 v7, v7
	v_exp_f32_e32 v0, v0
	v_exp_f32_e32 v1, v1
	v_exp_f32_e32 v2, v2
	v_exp_f32_e32 v3, v3
	v_add_f32_e32 v4, 1.0, v4
	v_add_f32_e32 v5, 1.0, v5
	v_add_f32_e32 v6, 1.0, v6
	v_add_f32_e32 v7, 1.0, v7
	v_add_f32_e32 v19, 1.0, v0
	v_add_f32_e32 v20, 1.0, v1
	v_add_f32_e32 v21, 1.0, v2
	v_add_f32_e32 v22, 1.0, v3
	v_rcp_f32_e32 v0, v4
	v_rcp_f32_e32 v1, v5
	v_rcp_f32_e32 v2, v6
	v_rcp_f32_e32 v3, v7
	v_rcp_f32_e32 v4, v19
	v_rcp_f32_e32 v5, v20
	v_rcp_f32_e32 v6, v21
	v_rcp_f32_e32 v7, v22
	v_mul_f32_e32 v18, v18, v18
	v_pk_mul_f32 v[0:1], v[18:19], v[0:1] op_sel_hi:[0,1]
	v_pk_mul_f32 v[2:3], v[18:19], v[2:3] op_sel_hi:[0,1]
	v_pk_mul_f32 v[4:5], v[18:19], v[4:5] op_sel_hi:[0,1]
	v_pk_mul_f32 v[6:7], v[18:19], v[6:7] op_sel_hi:[0,1]
	v_pk_mul_f32 v[0:1], v[12:13], v[0:1]
	v_pk_mul_f32 v[2:3], v[14:15], v[2:3]
	v_pk_mul_f32 v[4:5], v[8:9], v[4:5]
	v_pk_mul_f32 v[6:7], v[10:11], v[6:7]
	v_cvt_pk_bf16_f32 v0, v0, v1
	v_cvt_pk_bf16_f32 v1, v2, v3
	v_cvt_pk_bf16_f32 v2, v4, v5
	v_cvt_pk_bf16_f32 v3, v6, v7
	s_mov_b64 s[0:1], -1
	global_store_dwordx4 v[16:17], v[0:3], off
	s_cbranch_vccnz .LBB0_1231
	s_andn2_b64 vcc, exec, s[8:9]
	s_cbranch_vccnz .LBB0_1230
	s_barrier
	s_branch .LBB0_1230
